# v23 + strategy 7.5 instruction selection: SwiGLU GEMM epilogues (P8, P20) re-emitted with packed fp32 v_pk_mul_f32 / v_pk_add_f32 (same per-element operation order)
# baseline (speedup 1.0000x reference)
.LBB0_863:
	s_mov_b32 s98, 0xbfb8aa3b
	s_mov_b32 s99, 0xbfb8aa3b
	s_mov_b32 s100, 1.0
	s_mov_b32 s101, 1.0
	v_pk_mul_f32 v[170:171], v[122:123], s[98:99]
	v_pk_mul_f32 v[172:173], v[124:125], s[98:99]
	v_pk_mul_f32 v[174:175], v[126:127], s[98:99]
	v_pk_mul_f32 v[176:177], v[128:129], s[98:99]
	v_exp_f32_e32 v170, v170
	v_exp_f32_e32 v171, v171
	v_exp_f32_e32 v172, v172
	v_exp_f32_e32 v173, v173
	v_exp_f32_e32 v174, v174
	v_exp_f32_e32 v175, v175
	v_exp_f32_e32 v176, v176
	v_exp_f32_e32 v177, v177
	v_pk_add_f32 v[170:171], v[170:171], s[100:101]
	v_pk_add_f32 v[172:173], v[172:173], s[100:101]
	v_pk_add_f32 v[174:175], v[174:175], s[100:101]
	v_pk_add_f32 v[176:177], v[176:177], s[100:101]
	v_rcp_f32_e32 v170, v170
	v_rcp_f32_e32 v171, v171
	v_rcp_f32_e32 v172, v172
	v_rcp_f32_e32 v173, v173
	v_rcp_f32_e32 v174, v174
	v_rcp_f32_e32 v175, v175
	v_rcp_f32_e32 v176, v176
	v_rcp_f32_e32 v177, v177
	v_pk_mul_f32 v[122:123], v[122:123], v[170:171]
	v_pk_mul_f32 v[124:125], v[124:125], v[172:173]
	v_pk_mul_f32 v[126:127], v[126:127], v[174:175]
	v_pk_mul_f32 v[128:129], v[128:129], v[176:177]
	v_pk_mul_f32 v[122:123], v[122:123], v[114:115]
	v_pk_mul_f32 v[124:125], v[124:125], v[116:117]
	v_pk_mul_f32 v[126:127], v[126:127], v[118:119]
	v_pk_mul_f32 v[128:129], v[128:129], v[120:121]
	v_lshl_or_b32 v158, s2, 7, v152
	v_lshl_add_u32 v156, s24, 8, v150
	v_ashrrev_i32_e32 v159, 31, v158
	v_mov_b64_e32 v[146:147], s[10:11]
	v_mad_i64_i32 v[160:161], s[26:27], v156, s46, v[146:147]
	v_lshlrev_b64 v[114:115], 1, v[158:159]
	v_lshl_add_u64 v[120:121], v[160:161], 0, v[114:115]
	v_cvt_pk_bf16_f32 v116, v126, v127
	v_cvt_pk_bf16_f32 v117, v128, v129
	v_cvt_pk_bf16_f32 v118, v122, v123
	v_cvt_pk_bf16_f32 v119, v124, v125
	global_store_dwordx4 v[120:121], v[116:119], off
	v_pk_mul_f32 v[170:171], v[106:107], s[98:99]
	v_pk_mul_f32 v[172:173], v[108:109], s[98:99]
	v_pk_mul_f32 v[174:175], v[110:111], s[98:99]
	v_pk_mul_f32 v[176:177], v[112:113], s[98:99]
	v_exp_f32_e32 v170, v170
	v_exp_f32_e32 v171, v171
	v_exp_f32_e32 v172, v172
	v_exp_f32_e32 v173, v173
	v_exp_f32_e32 v174, v174
	v_exp_f32_e32 v175, v175
	v_exp_f32_e32 v176, v176
	v_exp_f32_e32 v177, v177
	v_pk_add_f32 v[170:171], v[170:171], s[100:101]
	v_pk_add_f32 v[172:173], v[172:173], s[100:101]
	v_pk_add_f32 v[174:175], v[174:175], s[100:101]
	v_pk_add_f32 v[176:177], v[176:177], s[100:101]
	v_rcp_f32_e32 v170, v170
	v_rcp_f32_e32 v171, v171
	v_rcp_f32_e32 v172, v172
	v_rcp_f32_e32 v173, v173
	v_rcp_f32_e32 v174, v174
	v_rcp_f32_e32 v175, v175
	v_rcp_f32_e32 v176, v176
	v_rcp_f32_e32 v177, v177
	v_pk_mul_f32 v[106:107], v[106:107], v[170:171]
	v_pk_mul_f32 v[108:109], v[108:109], v[172:173]
	v_pk_mul_f32 v[110:111], v[110:111], v[174:175]
	v_pk_mul_f32 v[112:113], v[112:113], v[176:177]
	v_pk_mul_f32 v[106:107], v[106:107], v[98:99]
	v_pk_mul_f32 v[108:109], v[108:109], v[100:101]
	v_pk_mul_f32 v[110:111], v[110:111], v[102:103]
	v_pk_mul_f32 v[112:113], v[112:113], v[104:105]
	s_andn2_b64 vcc, exec, s[6:7]
	s_mov_b64 s[6:7], -1
	v_or_b32_e32 v118, 16, v156
	v_mad_i64_i32 v[116:117], s[26:27], v118, s46, v[146:147]
	v_lshl_add_u64 v[102:103], v[116:117], 0, v[114:115]
	v_cvt_pk_bf16_f32 v98, v110, v111
	v_cvt_pk_bf16_f32 v99, v112, v113
	v_cvt_pk_bf16_f32 v100, v106, v107
	v_cvt_pk_bf16_f32 v101, v108, v109
	global_store_dwordx4 v[102:103], v[98:101], off
	v_pk_mul_f32 v[170:171], v[90:91], s[98:99]
	v_pk_mul_f32 v[172:173], v[92:93], s[98:99]
	v_pk_mul_f32 v[174:175], v[94:95], s[98:99]
	v_pk_mul_f32 v[176:177], v[96:97], s[98:99]
	v_exp_f32_e32 v170, v170
	v_exp_f32_e32 v171, v171
	v_exp_f32_e32 v172, v172
	v_exp_f32_e32 v173, v173
	v_exp_f32_e32 v174, v174
	v_exp_f32_e32 v175, v175
	v_exp_f32_e32 v176, v176
	v_exp_f32_e32 v177, v177
	v_pk_add_f32 v[170:171], v[170:171], s[100:101]
	v_pk_add_f32 v[172:173], v[172:173], s[100:101]
	v_pk_add_f32 v[174:175], v[174:175], s[100:101]
	v_pk_add_f32 v[176:177], v[176:177], s[100:101]
	v_rcp_f32_e32 v170, v170
	v_rcp_f32_e32 v171, v171
	v_rcp_f32_e32 v172, v172
	v_rcp_f32_e32 v173, v173
	v_rcp_f32_e32 v174, v174
	v_rcp_f32_e32 v175, v175
	v_rcp_f32_e32 v176, v176
	v_rcp_f32_e32 v177, v177
	v_pk_mul_f32 v[90:91], v[90:91], v[170:171]
	v_pk_mul_f32 v[92:93], v[92:93], v[172:173]
	v_pk_mul_f32 v[94:95], v[94:95], v[174:175]
	v_pk_mul_f32 v[96:97], v[96:97], v[176:177]
	v_pk_mul_f32 v[90:91], v[90:91], v[82:83]
	v_pk_mul_f32 v[92:93], v[92:93], v[84:85]
	v_pk_mul_f32 v[94:95], v[94:95], v[86:87]
	v_pk_mul_f32 v[96:97], v[96:97], v[88:89]
	s_nop 1
	v_or_b32_e32 v100, 32, v156
	v_mad_i64_i32 v[98:99], s[26:27], v100, s46, v[146:147]
	v_lshl_add_u64 v[86:87], v[98:99], 0, v[114:115]
	v_cvt_pk_bf16_f32 v82, v94, v95
	v_cvt_pk_bf16_f32 v83, v96, v97
	v_cvt_pk_bf16_f32 v84, v90, v91
	v_cvt_pk_bf16_f32 v85, v92, v93
	global_store_dwordx4 v[86:87], v[82:85], off
	v_pk_mul_f32 v[170:171], v[74:75], s[98:99]
	v_pk_mul_f32 v[172:173], v[76:77], s[98:99]
	v_pk_mul_f32 v[174:175], v[78:79], s[98:99]
	v_pk_mul_f32 v[176:177], v[80:81], s[98:99]
	v_exp_f32_e32 v170, v170
	v_exp_f32_e32 v171, v171
	v_exp_f32_e32 v172, v172
	v_exp_f32_e32 v173, v173
	v_exp_f32_e32 v174, v174
	v_exp_f32_e32 v175, v175
	v_exp_f32_e32 v176, v176
	v_exp_f32_e32 v177, v177
	v_pk_add_f32 v[170:171], v[170:171], s[100:101]
	v_pk_add_f32 v[172:173], v[172:173], s[100:101]
	v_pk_add_f32 v[174:175], v[174:175], s[100:101]
	v_pk_add_f32 v[176:177], v[176:177], s[100:101]
	v_rcp_f32_e32 v170, v170
	v_rcp_f32_e32 v171, v171
	v_rcp_f32_e32 v172, v172
	v_rcp_f32_e32 v173, v173
	v_rcp_f32_e32 v174, v174
	v_rcp_f32_e32 v175, v175
	v_rcp_f32_e32 v176, v176
	v_rcp_f32_e32 v177, v177
	v_pk_mul_f32 v[74:75], v[74:75], v[170:171]
	v_pk_mul_f32 v[76:77], v[76:77], v[172:173]
	v_pk_mul_f32 v[78:79], v[78:79], v[174:175]
	v_pk_mul_f32 v[80:81], v[80:81], v[176:177]
	v_pk_mul_f32 v[74:75], v[74:75], v[66:67]
	v_pk_mul_f32 v[76:77], v[76:77], v[68:69]
	v_pk_mul_f32 v[78:79], v[78:79], v[70:71]
	v_pk_mul_f32 v[80:81], v[80:81], v[72:73]
	s_nop 1
	v_or_b32_e32 v84, 48, v156
	v_mad_i64_i32 v[82:83], s[26:27], v84, s46, v[146:147]
	v_lshl_add_u64 v[70:71], v[82:83], 0, v[114:115]
	v_cvt_pk_bf16_f32 v66, v78, v79
	v_cvt_pk_bf16_f32 v67, v80, v81
	v_cvt_pk_bf16_f32 v68, v74, v75
	v_cvt_pk_bf16_f32 v69, v76, v77
	global_store_dwordx4 v[70:71], v[66:69], off
	v_pk_mul_f32 v[170:171], v[58:59], s[98:99]
	v_pk_mul_f32 v[172:173], v[60:61], s[98:99]
	v_pk_mul_f32 v[174:175], v[62:63], s[98:99]
	v_pk_mul_f32 v[176:177], v[64:65], s[98:99]
	v_exp_f32_e32 v170, v170
	v_exp_f32_e32 v171, v171
	v_exp_f32_e32 v172, v172
	v_exp_f32_e32 v173, v173
	v_exp_f32_e32 v174, v174
	v_exp_f32_e32 v175, v175
	v_exp_f32_e32 v176, v176
	v_exp_f32_e32 v177, v177
	v_pk_add_f32 v[170:171], v[170:171], s[100:101]
	v_pk_add_f32 v[172:173], v[172:173], s[100:101]
	v_pk_add_f32 v[174:175], v[174:175], s[100:101]
	v_pk_add_f32 v[176:177], v[176:177], s[100:101]
	v_rcp_f32_e32 v170, v170
	v_rcp_f32_e32 v171, v171
	v_rcp_f32_e32 v172, v172
	v_rcp_f32_e32 v173, v173
	v_rcp_f32_e32 v174, v174
	v_rcp_f32_e32 v175, v175
	v_rcp_f32_e32 v176, v176
	v_rcp_f32_e32 v177, v177
	v_pk_mul_f32 v[58:59], v[58:59], v[170:171]
	v_pk_mul_f32 v[60:61], v[60:61], v[172:173]
	v_pk_mul_f32 v[62:63], v[62:63], v[174:175]
	v_pk_mul_f32 v[64:65], v[64:65], v[176:177]
	v_pk_mul_f32 v[58:59], v[58:59], v[50:51]
	v_pk_mul_f32 v[60:61], v[60:61], v[52:53]
	v_pk_mul_f32 v[62:63], v[62:63], v[54:55]
	v_pk_mul_f32 v[64:65], v[64:65], v[56:57]
	s_nop 1
	v_add_u32_e32 v68, 0x80, v156
	v_mad_i64_i32 v[66:67], s[26:27], v68, s46, v[146:147]
	v_lshl_add_u64 v[54:55], v[66:67], 0, v[114:115]
	v_cvt_pk_bf16_f32 v50, v62, v63
	v_cvt_pk_bf16_f32 v51, v64, v65
	v_cvt_pk_bf16_f32 v52, v58, v59
	v_cvt_pk_bf16_f32 v53, v60, v61
	global_store_dwordx4 v[54:55], v[50:53], off
	v_pk_mul_f32 v[170:171], v[42:43], s[98:99]
	v_pk_mul_f32 v[172:173], v[44:45], s[98:99]
	v_pk_mul_f32 v[174:175], v[46:47], s[98:99]
	v_pk_mul_f32 v[176:177], v[48:49], s[98:99]
	v_exp_f32_e32 v170, v170
	v_exp_f32_e32 v171, v171
	v_exp_f32_e32 v172, v172
	v_exp_f32_e32 v173, v173
	v_exp_f32_e32 v174, v174
	v_exp_f32_e32 v175, v175
	v_exp_f32_e32 v176, v176
	v_exp_f32_e32 v177, v177
	v_pk_add_f32 v[170:171], v[170:171], s[100:101]
	v_pk_add_f32 v[172:173], v[172:173], s[100:101]
	v_pk_add_f32 v[174:175], v[174:175], s[100:101]
	v_pk_add_f32 v[176:177], v[176:177], s[100:101]
	v_rcp_f32_e32 v170, v170
	v_rcp_f32_e32 v171, v171
	v_rcp_f32_e32 v172, v172
	v_rcp_f32_e32 v173, v173
	v_rcp_f32_e32 v174, v174
	v_rcp_f32_e32 v175, v175
	v_rcp_f32_e32 v176, v176
	v_rcp_f32_e32 v177, v177
	v_pk_mul_f32 v[42:43], v[42:43], v[170:171]
	v_pk_mul_f32 v[44:45], v[44:45], v[172:173]
	v_pk_mul_f32 v[46:47], v[46:47], v[174:175]
	v_pk_mul_f32 v[48:49], v[48:49], v[176:177]
	v_pk_mul_f32 v[42:43], v[42:43], v[34:35]
	v_pk_mul_f32 v[44:45], v[44:45], v[36:37]
	v_pk_mul_f32 v[46:47], v[46:47], v[38:39]
	v_pk_mul_f32 v[48:49], v[48:49], v[40:41]
	s_nop 1
	v_add_u32_e32 v52, 0x90, v156
	v_mad_i64_i32 v[50:51], s[26:27], v52, s46, v[146:147]
	v_lshl_add_u64 v[38:39], v[50:51], 0, v[114:115]
	v_cvt_pk_bf16_f32 v34, v46, v47
	v_cvt_pk_bf16_f32 v35, v48, v49
	v_cvt_pk_bf16_f32 v36, v42, v43
	v_cvt_pk_bf16_f32 v37, v44, v45
	global_store_dwordx4 v[38:39], v[34:37], off
	v_pk_mul_f32 v[170:171], v[26:27], s[98:99]
	v_pk_mul_f32 v[172:173], v[28:29], s[98:99]
	v_pk_mul_f32 v[174:175], v[30:31], s[98:99]
	v_pk_mul_f32 v[176:177], v[32:33], s[98:99]
	v_exp_f32_e32 v170, v170
	v_exp_f32_e32 v171, v171
	v_exp_f32_e32 v172, v172
	v_exp_f32_e32 v173, v173
	v_exp_f32_e32 v174, v174
	v_exp_f32_e32 v175, v175
	v_exp_f32_e32 v176, v176
	v_exp_f32_e32 v177, v177
	v_pk_add_f32 v[170:171], v[170:171], s[100:101]
	v_pk_add_f32 v[172:173], v[172:173], s[100:101]
	v_pk_add_f32 v[174:175], v[174:175], s[100:101]
	v_pk_add_f32 v[176:177], v[176:177], s[100:101]
	v_rcp_f32_e32 v170, v170
	v_rcp_f32_e32 v171, v171
	v_rcp_f32_e32 v172, v172
	v_rcp_f32_e32 v173, v173
	v_rcp_f32_e32 v174, v174
	v_rcp_f32_e32 v175, v175
	v_rcp_f32_e32 v176, v176
	v_rcp_f32_e32 v177, v177
	v_pk_mul_f32 v[26:27], v[26:27], v[170:171]
	v_pk_mul_f32 v[28:29], v[28:29], v[172:173]
	v_pk_mul_f32 v[30:31], v[30:31], v[174:175]
	v_pk_mul_f32 v[32:33], v[32:33], v[176:177]
	v_pk_mul_f32 v[26:27], v[26:27], v[18:19]
	v_pk_mul_f32 v[28:29], v[28:29], v[20:21]
	v_pk_mul_f32 v[30:31], v[30:31], v[22:23]
	v_pk_mul_f32 v[32:33], v[32:33], v[24:25]
	s_nop 1
	v_add_u32_e32 v36, 0xa0, v156
	v_mad_i64_i32 v[34:35], s[26:27], v36, s46, v[146:147]
	v_lshl_add_u64 v[22:23], v[34:35], 0, v[114:115]
	v_cvt_pk_bf16_f32 v18, v30, v31
	v_cvt_pk_bf16_f32 v19, v32, v33
	v_cvt_pk_bf16_f32 v20, v26, v27
	v_cvt_pk_bf16_f32 v21, v28, v29
	global_store_dwordx4 v[22:23], v[18:21], off
	v_pk_mul_f32 v[170:171], v[10:11], s[98:99]
	v_pk_mul_f32 v[172:173], v[12:13], s[98:99]
	v_pk_mul_f32 v[174:175], v[14:15], s[98:99]
	v_pk_mul_f32 v[176:177], v[16:17], s[98:99]
	v_exp_f32_e32 v170, v170
	v_exp_f32_e32 v171, v171
	v_exp_f32_e32 v172, v172
	v_exp_f32_e32 v173, v173
	v_exp_f32_e32 v174, v174
	v_exp_f32_e32 v175, v175
	v_exp_f32_e32 v176, v176
	v_exp_f32_e32 v177, v177
	v_pk_add_f32 v[170:171], v[170:171], s[100:101]
	v_pk_add_f32 v[172:173], v[172:173], s[100:101]
	v_pk_add_f32 v[174:175], v[174:175], s[100:101]
	v_pk_add_f32 v[176:177], v[176:177], s[100:101]
	v_rcp_f32_e32 v170, v170
	v_rcp_f32_e32 v171, v171
	v_rcp_f32_e32 v172, v172
	v_rcp_f32_e32 v173, v173
	v_rcp_f32_e32 v174, v174
	v_rcp_f32_e32 v175, v175
	v_rcp_f32_e32 v176, v176
	v_rcp_f32_e32 v177, v177
	v_pk_mul_f32 v[10:11], v[10:11], v[170:171]
	v_pk_mul_f32 v[12:13], v[12:13], v[172:173]
	v_pk_mul_f32 v[14:15], v[14:15], v[174:175]
	v_pk_mul_f32 v[16:17], v[16:17], v[176:177]
	v_pk_mul_f32 v[10:11], v[10:11], v[2:3]
	v_pk_mul_f32 v[12:13], v[12:13], v[4:5]
	v_pk_mul_f32 v[14:15], v[14:15], v[6:7]
	v_pk_mul_f32 v[16:17], v[16:17], v[8:9]
	s_nop 1
	v_add_u32_e32 v20, 0xb0, v156
	v_mad_i64_i32 v[18:19], s[26:27], v20, s46, v[146:147]
	v_lshl_add_u64 v[6:7], v[18:19], 0, v[114:115]
	v_cvt_pk_bf16_f32 v2, v14, v15
	v_cvt_pk_bf16_f32 v3, v16, v17
	v_cvt_pk_bf16_f32 v4, v10, v11
	v_cvt_pk_bf16_f32 v5, v12, v13
	global_store_dwordx4 v[6:7], v[2:5], off
	s_cbranch_vccnz .LBB0_856
	s_andn2_b64 vcc, exec, s[8:9]
	s_cbranch_vccnz .LBB0_855
	s_barrier
	s_branch .LBB0_855
